# 64-bit zeroing: in-proj and gate GEMM accumulator zero blocks use 64 v_mov_b64 instead of 128 v_mov_b32
# speedup vs baseline: 1.0021x; 1.0021x over previous
.LBB0_132:
	s_ashr_i32 s59, s58, 31
	s_lshl_b64 s[28:29], s[58:59], 19
	s_add_u32 s60, s18, s28
	s_addc_u32 s61, s19, s29
	s_and_b64 s[28:29], s[0:1], exec
	s_cselect_b32 s5, s61, s67
	s_cselect_b32 s59, s60, s66
	s_ashr_i32 s57, s56, 31
	s_lshl_b64 s[28:29], s[56:57], 19
	s_add_u32 s62, s6, s28
	s_addc_u32 s63, s7, s29
	s_and_b64 s[28:29], s[0:1], exec
	s_cselect_b32 s57, s63, s69
	s_cselect_b32 s65, s62, s68
	s_add_u32 s66, s66, 0x40080
	s_addc_u32 s67, s67, 0
	s_add_u32 s88, s68, 0x100
	v_mov_b64_e32 v[0:1], 0
	v_mov_b64_e32 v[2:3], 0
	v_mov_b64_e32 v[4:5], 0
	v_mov_b64_e32 v[6:7], 0
	v_mov_b64_e32 v[8:9], 0
	v_mov_b64_e32 v[10:11], 0
	v_mov_b64_e32 v[12:13], 0
	v_mov_b64_e32 v[14:15], 0
	v_mov_b64_e32 v[16:17], 0
	v_mov_b64_e32 v[18:19], 0
	v_mov_b64_e32 v[20:21], 0
	v_mov_b64_e32 v[22:23], 0
	v_mov_b64_e32 v[24:25], 0
	v_mov_b64_e32 v[26:27], 0
	v_mov_b64_e32 v[28:29], 0
	v_mov_b64_e32 v[30:31], 0
	v_mov_b64_e32 v[32:33], 0
	v_mov_b64_e32 v[34:35], 0
	v_mov_b64_e32 v[36:37], 0
	v_mov_b64_e32 v[38:39], 0
	v_mov_b64_e32 v[40:41], 0
	v_mov_b64_e32 v[42:43], 0
	v_mov_b64_e32 v[44:45], 0
	v_mov_b64_e32 v[46:47], 0
	v_mov_b64_e32 v[48:49], 0
	v_mov_b64_e32 v[50:51], 0
	v_mov_b64_e32 v[52:53], 0
	v_mov_b64_e32 v[54:55], 0
	v_mov_b64_e32 v[56:57], 0
	v_mov_b64_e32 v[58:59], 0
	v_mov_b64_e32 v[60:61], 0
	v_mov_b64_e32 v[62:63], 0
	v_mov_b64_e32 v[64:65], 0
	v_mov_b64_e32 v[66:67], 0
	v_mov_b64_e32 v[68:69], 0
	v_mov_b64_e32 v[70:71], 0
	v_mov_b64_e32 v[72:73], 0
	v_mov_b64_e32 v[74:75], 0
	v_mov_b64_e32 v[76:77], 0
	v_mov_b64_e32 v[78:79], 0
	v_mov_b64_e32 v[80:81], 0
	v_mov_b64_e32 v[82:83], 0
	v_mov_b64_e32 v[84:85], 0
	v_mov_b64_e32 v[86:87], 0
	v_mov_b64_e32 v[88:89], 0
	v_mov_b64_e32 v[90:91], 0
	v_mov_b64_e32 v[92:93], 0
	v_mov_b64_e32 v[94:95], 0
	v_mov_b64_e32 v[96:97], 0
	v_mov_b64_e32 v[98:99], 0
	v_mov_b64_e32 v[100:101], 0
	v_mov_b64_e32 v[102:103], 0
	v_mov_b64_e32 v[104:105], 0
	v_mov_b64_e32 v[106:107], 0
	v_mov_b64_e32 v[108:109], 0
	v_mov_b64_e32 v[110:111], 0
	v_mov_b64_e32 v[112:113], 0
	v_mov_b64_e32 v[114:115], 0
	v_mov_b64_e32 v[116:117], 0
	v_mov_b64_e32 v[118:119], 0
	v_mov_b64_e32 v[120:121], 0
	v_mov_b64_e32 v[122:123], 0
	v_mov_b64_e32 v[124:125], 0
	v_mov_b64_e32 v[126:127], 0
	s_addc_u32 s89, s69, 0
	s_mov_b32 s90, -2

.LBB0_473:
	s_ashr_i32 s21, s20, 31
	s_lshl_b64 s[22:23], s[20:21], 19
	s_add_u32 s22, s16, s22
	s_addc_u32 s23, s17, s23
	s_and_b64 s[24:25], s[0:1], exec
	s_cselect_b32 s21, s23, s29
	s_cselect_b32 s50, s22, s28
	s_ashr_i32 s19, s18, 31
	s_lshl_b64 s[24:25], s[18:19], 19
	s_add_u32 s24, s34, s24
	s_addc_u32 s25, s35, s25
	s_and_b64 s[38:39], s[0:1], exec
	s_cselect_b32 s19, s25, s37
	s_cselect_b32 s51, s24, s36
	s_add_u32 s28, s28, 0x40080
	s_addc_u32 s29, s29, 0
	s_add_u32 s52, s36, 0x100
	v_mov_b64_e32 v[0:1], 0
	v_mov_b64_e32 v[2:3], 0
	v_mov_b64_e32 v[4:5], 0
	v_mov_b64_e32 v[6:7], 0
	v_mov_b64_e32 v[8:9], 0
	v_mov_b64_e32 v[10:11], 0
	v_mov_b64_e32 v[12:13], 0
	v_mov_b64_e32 v[14:15], 0
	v_mov_b64_e32 v[16:17], 0
	v_mov_b64_e32 v[18:19], 0
	v_mov_b64_e32 v[20:21], 0
	v_mov_b64_e32 v[22:23], 0
	v_mov_b64_e32 v[24:25], 0
	v_mov_b64_e32 v[26:27], 0
	v_mov_b64_e32 v[28:29], 0
	v_mov_b64_e32 v[30:31], 0
	v_mov_b64_e32 v[32:33], 0
	v_mov_b64_e32 v[34:35], 0
	v_mov_b64_e32 v[36:37], 0
	v_mov_b64_e32 v[38:39], 0
	v_mov_b64_e32 v[40:41], 0
	v_mov_b64_e32 v[42:43], 0
	v_mov_b64_e32 v[44:45], 0
	v_mov_b64_e32 v[46:47], 0
	v_mov_b64_e32 v[48:49], 0
	v_mov_b64_e32 v[50:51], 0
	v_mov_b64_e32 v[52:53], 0
	v_mov_b64_e32 v[54:55], 0
	v_mov_b64_e32 v[56:57], 0
	v_mov_b64_e32 v[58:59], 0
	v_mov_b64_e32 v[60:61], 0
	v_mov_b64_e32 v[62:63], 0
	v_mov_b64_e32 v[64:65], 0
	v_mov_b64_e32 v[66:67], 0
	v_mov_b64_e32 v[68:69], 0
	v_mov_b64_e32 v[70:71], 0
	v_mov_b64_e32 v[72:73], 0
	v_mov_b64_e32 v[74:75], 0
	v_mov_b64_e32 v[76:77], 0
	v_mov_b64_e32 v[78:79], 0
	v_mov_b64_e32 v[80:81], 0
	v_mov_b64_e32 v[82:83], 0
	v_mov_b64_e32 v[84:85], 0
	v_mov_b64_e32 v[86:87], 0
	v_mov_b64_e32 v[88:89], 0
	v_mov_b64_e32 v[90:91], 0
	v_mov_b64_e32 v[92:93], 0
	v_mov_b64_e32 v[94:95], 0
	v_mov_b64_e32 v[96:97], 0
	v_mov_b64_e32 v[98:99], 0
	v_mov_b64_e32 v[100:101], 0
	v_mov_b64_e32 v[102:103], 0
	v_mov_b64_e32 v[104:105], 0
	v_mov_b64_e32 v[106:107], 0
	v_mov_b64_e32 v[108:109], 0
	v_mov_b64_e32 v[110:111], 0
	v_mov_b64_e32 v[112:113], 0
	v_mov_b64_e32 v[114:115], 0
	v_mov_b64_e32 v[116:117], 0
	v_mov_b64_e32 v[118:119], 0
	v_mov_b64_e32 v[120:121], 0
	v_mov_b64_e32 v[122:123], 0
	v_mov_b64_e32 v[124:125], 0
	v_mov_b64_e32 v[126:127], 0
	s_addc_u32 s53, s37, 0
	s_mov_b32 s54, -2
	s_waitcnt vmcnt(0)
